# O1 + E3 + O3 wide phases staggered 12us for the second co-resident workgroup
# speedup vs baseline: 1.0068x; 1.0008x over previous
;   DI u16* Wt_out_e() const { return (u16*)(ws + WS_Wt_out_e); }
;   DI u16* A2() const { return (u16*)(ws + WS_A2); }
; DI TileSched tile_sched(int ntot) {
;   TileSched ts;
;   if ((gridDim.x & 7) == 0) {
;     const int xcd = blockIdx.x & 7, j = blockIdx.x >> 3, nb = gridDim.x >> 3;
;     ts.t = (int)(((long)ntot * xcd) >> 3) + j; ts.hi = (int)(((long)ntot * (xcd + 1)) >> 3); ts.step = nb;
;   } else { ts.t = blockIdx.x; ts.hi = ntot; ts.step = gridDim.x; }
;   return ts;
; }
; __global__ void __launch_bounds__(256, 2) fwd_megakernel(Params p) {
;     ...
;   for (TileSched ts = tile_sched(128 * 4); ts.t < ts.hi; ts.t += ts.step) {
;     const int mt = ts.t >> 2, n2 = ts.t & 3;
;     gemm_tile_wide<1024>(p.A2(), 1024, p.Wt_out_e(), 1024, mt * 128, n2 * 256, smem, [&](int half) { epi_out(p, mt, 2 * n2 + half, (const float*)smem, 0); });
.LBB0_639:
	v_readlane_b32 s0, v247, 4
	v_readlane_b32 s1, v247, 5
	s_mov_b32 s2, s0
	s_and_b32 s0, s0, 7
	s_lshr_b32 s1, s2, 3
	v_readlane_b32 s2, v247, 6
	s_lshr_b32 s4, s2, 3
	s_lshl_b32 s2, s0, 6
	s_lshl_b32 s0, s0, 9
	s_addk_i32 s0, 0x200
	s_add_i32 s5, s2, s1
	s_lshr_b32 s18, s0, 3
	v_readlane_b32 s3, v247, 7
	s_cmp_ge_i32 s5, s18
	s_cbranch_scc1 .LBB0_776
.LBB0_640:
	s_getreg_b32 s99, hwreg(HW_REG_LDS_ALLOC, 0, 12)
	s_cmp_eq_u32 s99, 0
	s_cbranch_scc1 .Lstag_e3
	s_sleep 127
	s_sleep 127
	s_sleep 127
.Lstag_e3:
	s_add_u32 s6, s86, 0x27c8000
	s_addc_u32 s7, s87, 0
	s_add_u32 s8, s86, 0x18311000
	s_addc_u32 s9, s87, 0
	s_add_u32 s10, s86, 0xbcf0040
	s_addc_u32 s11, s87, 0
	s_lshl_b32 s19, s5, 5
	s_lshl_b32 s21, s4, 5
	s_add_u32 s12, s86, 0x27c8040
	s_addc_u32 s13, s87, 0
	s_lshl_b32 s22, s5, 8
	s_lshl_b32 s23, s4, 8
	v_mov_b32_e32 v137, 0
	s_mov_b64 s[14:15], 0x40000
	s_mov_b64 s[16:17], 0x60000
	s_movk_i32 s24, 0x210
	s_movk_i32 s25, 0x3fff
	s_mov_b32 s20, 0x3fb504f3
	s_branch .LBB0_642

;   DI u16* Wt_out_o() const { return (u16*)(ws + WS_Wt_out_o); }
;   DI u16* A2() const { return (u16*)(ws + WS_A2); }
; DI TileSched tile_sched(int ntot) {
;   TileSched ts;
;   if ((gridDim.x & 7) == 0) {
;     const int xcd = blockIdx.x & 7, j = blockIdx.x >> 3, nb = gridDim.x >> 3;
;     ts.t = (int)(((long)ntot * xcd) >> 3) + j; ts.hi = (int)(((long)ntot * (xcd + 1)) >> 3); ts.step = nb;
;   } else { ts.t = blockIdx.x; ts.hi = ntot; ts.step = gridDim.x; }
;   return ts;
; }
; __global__ void __launch_bounds__(256, 2) fwd_megakernel(Params p) {
;     ...
;   for (TileSched ts = tile_sched(128 * 4); ts.t < ts.hi; ts.t += ts.step) {
;     const int mt = ts.t >> 2, n2 = ts.t & 3;
;     gemm_tile_wide<1024>(p.A2(), 1024, p.Wt_out_o(), 1024, mt * 128, n2 * 256, smem, [&](int half) { epi_out(p, mt, 2 * n2 + half, (const float*)smem, 1); });
.LBB0_2047:
	v_readlane_b32 s0, v247, 4
	v_readlane_b32 s1, v247, 5
	s_mov_b32 s2, s0
	s_and_b32 s0, s0, 7
	s_lshr_b32 s1, s2, 3
	v_readlane_b32 s2, v247, 6
	s_lshr_b32 s4, s2, 3
	s_lshl_b32 s2, s0, 6
	s_lshl_b32 s0, s0, 9
	s_addk_i32 s0, 0x200
	s_add_i32 s5, s2, s1
	s_lshr_b32 s18, s0, 3
	v_readlane_b32 s3, v247, 7
	s_cmp_ge_i32 s5, s18
	s_cbranch_scc1 .LBB0_2056
.LBB0_2048:
	s_getreg_b32 s99, hwreg(HW_REG_LDS_ALLOC, 0, 12)
	s_cmp_eq_u32 s99, 0
	s_cbranch_scc1 .Lstag_o3
	s_sleep 127
	s_sleep 127
	s_sleep 127
.Lstag_o3:
	s_add_u32 s6, s86, 0x31c8000
	s_addc_u32 s7, s87, 0
	s_add_u32 s8, s86, 0xddf0000
	s_addc_u32 s9, s87, 0
	s_add_u32 s10, s86, 0x18311000
	s_addc_u32 s11, s87, 0
	s_add_u32 s12, s86, 0xbcf0040
	s_addc_u32 s13, s87, 0
	s_lshl_b32 s19, s5, 5
	s_lshl_b32 s23, s4, 5
	s_add_u32 s14, s86, 0x31c8040
	s_addc_u32 s15, s87, 0
	s_lshl_b32 s24, s5, 8
	s_lshl_b32 s25, s4, 8
	v_mov_b32_e32 v129, 0
	s_mov_b64 s[16:17], 0x40000
	s_mov_b64 s[20:21], 0x60000
	s_movk_i32 s26, 0x210
	s_mov_b32 s22, 0x3fb504f3
	s_branch .LBB0_2050
